# grid barrier release: all workgroups poll the top generation word directly; per-XCD generation hop removed
# speedup vs baseline: 1.0281x; 1.0003x over previous
.LBB0_359:
	s_lshl_b32 s0, s2, 8
	s_add_u32 s0, s42, s0
	s_addc_u32 s1, s43, 0
	v_mov_b32_e32 v1, s0
	v_add_co_u32_e32 v6, vcc, 0x101000, v1
	v_mov_b32_e32 v1, s1
	s_nop 0
	v_addc_co_u32_e32 v7, vcc, 0, v1, vcc
	v_mov_b32_e32 v1, 1
	global_atomic_add v1, v[6:7], v1, off offset:1024 sc0
	v_cvt_f32_u32_e32 v3, v4
	v_sub_u32_e32 v5, 0, v4
	s_add_u32 s3, s0, 0x100000
	s_addc_u32 s2, s1, 0
	v_rcp_iflag_f32_e32 v3, v3
	s_waitcnt vmcnt(0) lgkmcnt(0)
	v_add_u32_e32 v6, 1, v1
	v_mul_f32_e32 v3, 0x4f7ffffe, v3
	v_cvt_u32_f32_e32 v3, v3
	v_mul_lo_u32 v5, v5, v3
	v_mul_hi_u32 v5, v3, v5
	v_add_u32_e32 v3, v3, v5
	v_mul_hi_u32 v3, v1, v3
	v_mul_lo_u32 v5, v3, v4
	v_sub_u32_e32 v1, v1, v5
	v_add_u32_e32 v7, 1, v3
	v_cmp_ge_u32_e32 vcc, v1, v4
	v_sub_u32_e32 v5, v1, v4
	s_nop 0
	v_cndmask_b32_e32 v3, v3, v7, vcc
	v_cndmask_b32_e32 v1, v1, v5, vcc
	v_add_u32_e32 v5, 1, v3
	v_cmp_ge_u32_e32 vcc, v1, v4
	s_nop 1
	v_cndmask_b32_e32 v1, v3, v5, vcc
	v_mad_u64_u32 v[4:5], s[0:1], v4, v1, v[4:5]
	v_cmp_ne_u32_e32 vcc, v6, v4
	s_and_saveexec_b64 s[0:1], vcc
	s_xor_b64 s[0:1], exec, s[0:1]
	s_cbranch_execz .LBB0_372
	v_mov_b32_e32 v2, s42
	v_add_co_u32_e32 v2, vcc, 0x103000, v2
	v_mov_b32_e32 v3, s43
	s_nop 0
	v_addc_co_u32_e32 v3, vcc, 0, v3, vcc
	global_load_dword v2, v[2:3], off offset:1280 sc1
	s_add_u32 s8, s42, 0x103500
	s_addc_u32 s9, s43, 0
	s_waitcnt vmcnt(0) lgkmcnt(0)
	v_cmp_eq_u32_e32 vcc, v2, v1
	s_and_saveexec_b64 s[4:5], vcc
	s_cbranch_execz .LBB0_371
	s_add_u32 s6, s42, 0x100200
	s_addc_u32 s7, s43, 0
	s_mov_b32 s14, 1
	s_mov_b64 s[10:11], 0
	s_branch .LBB0_363

.LBB0_387:
	s_or_b64 exec, exec, s[0:1]
	v_mov_b32_e32 v1, s3
	v_add_co_u32_e32 v2, vcc, 0x2000, v1
	v_mov_b32_e32 v1, s2
	s_nop 0
	v_addc_co_u32_e32 v3, vcc, 0, v1, vcc
	v_mov_b32_e32 v1, 1
	s_waitcnt vmcnt(0) lgkmcnt(0)
	buffer_inv sc1
	s_waitcnt vmcnt(0)

.LBB0_433:
	s_lshl_b32 s1, s1, 8
	s_add_u32 s1, s46, s1
	s_addc_u32 s3, s47, 0
	v_mov_b32_e32 v1, s1
	v_add_co_u32_e32 v4, vcc, 0x101000, v1
	v_mov_b32_e32 v1, s3
	s_nop 0
	v_addc_co_u32_e32 v5, vcc, 0, v1, vcc
	v_mov_b32_e32 v1, 1
	global_atomic_add v1, v[4:5], v1, off offset:1024 sc0
	v_cvt_f32_u32_e32 v3, v2
	v_sub_u32_e32 v4, 0, v2
	s_add_u32 s2, s1, 0x100000
	s_addc_u32 s1, s3, 0
	v_rcp_iflag_f32_e32 v3, v3
	s_nop 0
	v_mul_f32_e32 v3, 0x4f7ffffe, v3
	v_cvt_u32_f32_e32 v3, v3
	v_mul_lo_u32 v4, v4, v3
	v_mul_hi_u32 v4, v3, v4
	v_add_u32_e32 v3, v3, v4
	s_waitcnt vmcnt(0) lgkmcnt(0)
	v_mul_hi_u32 v3, v1, v3
	v_mul_lo_u32 v5, v3, v2
	v_add_u32_e32 v4, 1, v1
	v_sub_u32_e32 v1, v1, v5
	v_add_u32_e32 v6, 1, v3
	v_cmp_ge_u32_e32 vcc, v1, v2
	v_sub_u32_e32 v5, v1, v2
	s_nop 0
	v_cndmask_b32_e32 v3, v3, v6, vcc
	v_cndmask_b32_e32 v1, v1, v5, vcc
	v_add_u32_e32 v5, 1, v3
	v_cmp_ge_u32_e32 vcc, v1, v2
	s_nop 1
	v_cndmask_b32_e32 v1, v3, v5, vcc
	v_mad_u64_u32 v[2:3], s[4:5], v2, v1, v[2:3]
	v_cmp_ne_u32_e32 vcc, v4, v2
	s_and_saveexec_b64 s[4:5], vcc
	s_xor_b64 s[4:5], exec, s[4:5]
	s_cbranch_execz .LBB0_446
	v_mov_b32_e32 v0, s46
	v_add_co_u32_e32 v2, vcc, 0x103000, v0
	v_mov_b32_e32 v0, s47
	s_nop 0
	v_addc_co_u32_e32 v3, vcc, 0, v0, vcc
	global_load_dword v0, v[2:3], off offset:1280 sc1
	s_add_u32 s10, s46, 0x103500
	s_addc_u32 s11, s47, 0
	s_waitcnt vmcnt(0) lgkmcnt(0)
	v_cmp_eq_u32_e32 vcc, v0, v1
	s_and_saveexec_b64 s[6:7], vcc
	s_cbranch_execz .LBB0_445
	s_add_u32 s8, s46, 0x100200
	s_addc_u32 s9, s47, 0
	s_mov_b32 s3, 1
	s_mov_b64 s[12:13], 0
	s_branch .LBB0_437

.LBB0_461:
	s_or_b64 exec, exec, s[4:5]
	v_mov_b32_e32 v0, s2
	v_add_co_u32_e32 v0, vcc, 0x2000, v0
	v_mov_b32_e32 v1, s1
	s_nop 0
	v_addc_co_u32_e32 v1, vcc, 0, v1, vcc
	v_mov_b32_e32 v2, 1
	s_waitcnt vmcnt(0) lgkmcnt(0)
	buffer_inv sc1
	s_waitcnt vmcnt(0)

.LBB0_525:
	s_lshl_b32 s1, s1, 8
	s_add_u32 s1, s4, s1
	s_addc_u32 s3, s5, 0
	v_mov_b32_e32 v1, s1
	v_add_co_u32_e32 v4, vcc, 0x101000, v1
	v_mov_b32_e32 v1, s3
	s_nop 0
	v_addc_co_u32_e32 v5, vcc, 0, v1, vcc
	v_mov_b32_e32 v1, 1
	global_atomic_add v1, v[4:5], v1, off offset:1024 sc0
	v_cvt_f32_u32_e32 v3, v2
	v_sub_u32_e32 v4, 0, v2
	s_add_u32 s2, s1, 0x100000
	s_addc_u32 s1, s3, 0
	v_rcp_iflag_f32_e32 v3, v3
	s_nop 0
	v_mul_f32_e32 v3, 0x4f7ffffe, v3
	v_cvt_u32_f32_e32 v3, v3
	v_mul_lo_u32 v4, v4, v3
	v_mul_hi_u32 v4, v3, v4
	v_add_u32_e32 v3, v3, v4
	s_waitcnt vmcnt(0) lgkmcnt(0)
	v_mul_hi_u32 v3, v1, v3
	v_mul_lo_u32 v5, v3, v2
	v_add_u32_e32 v4, 1, v1
	v_sub_u32_e32 v1, v1, v5
	v_add_u32_e32 v6, 1, v3
	v_cmp_ge_u32_e32 vcc, v1, v2
	v_sub_u32_e32 v5, v1, v2
	s_nop 0
	v_cndmask_b32_e32 v3, v3, v6, vcc
	v_cndmask_b32_e32 v1, v1, v5, vcc
	v_add_u32_e32 v5, 1, v3
	v_cmp_ge_u32_e32 vcc, v1, v2
	s_nop 1
	v_cndmask_b32_e32 v1, v3, v5, vcc
	v_mad_u64_u32 v[2:3], s[6:7], v2, v1, v[2:3]
	v_cmp_ne_u32_e32 vcc, v4, v2
	s_and_saveexec_b64 s[6:7], vcc
	s_xor_b64 s[6:7], exec, s[6:7]
	s_cbranch_execz .LBB0_538
	v_mov_b32_e32 v0, s4
	v_add_co_u32_e32 v2, vcc, 0x103000, v0
	v_mov_b32_e32 v0, s5
	s_nop 0
	v_addc_co_u32_e32 v3, vcc, 0, v0, vcc
	global_load_dword v0, v[2:3], off offset:1280 sc1
	s_add_u32 s12, s4, 0x103500
	s_addc_u32 s13, s5, 0
	s_waitcnt vmcnt(0) lgkmcnt(0)
	v_cmp_eq_u32_e32 vcc, v0, v1
	s_and_saveexec_b64 s[8:9], vcc
	s_cbranch_execz .LBB0_537
	s_add_u32 s10, s4, 0x100200
	s_addc_u32 s11, s5, 0
	s_mov_b32 s3, 1
	s_mov_b64 s[16:17], 0
	s_branch .LBB0_529

.LBB0_716:
	s_lshl_b32 s3, s3, 8
	s_add_u32 s3, s4, s3
	s_addc_u32 s6, s5, 0
	v_mov_b32_e32 v1, s3
	v_add_co_u32_e32 v4, vcc, 0x101000, v1
	v_mov_b32_e32 v1, s6
	s_nop 0
	v_addc_co_u32_e32 v5, vcc, 0, v1, vcc
	v_mov_b32_e32 v1, 1
	global_atomic_add v1, v[4:5], v1, off offset:1024 sc0
	v_cvt_f32_u32_e32 v3, v2
	v_sub_u32_e32 v4, 0, v2
	s_add_u32 s14, s3, 0x100000
	s_addc_u32 s3, s6, 0
	v_rcp_iflag_f32_e32 v3, v3
	s_nop 0
	v_mul_f32_e32 v3, 0x4f7ffffe, v3
	v_cvt_u32_f32_e32 v3, v3
	v_mul_lo_u32 v4, v4, v3
	v_mul_hi_u32 v4, v3, v4
	v_add_u32_e32 v3, v3, v4
	s_waitcnt vmcnt(0) lgkmcnt(0)
	v_mul_hi_u32 v3, v1, v3
	v_mul_lo_u32 v5, v3, v2
	v_add_u32_e32 v4, 1, v1
	v_sub_u32_e32 v1, v1, v5
	v_add_u32_e32 v6, 1, v3
	v_cmp_ge_u32_e32 vcc, v1, v2
	v_sub_u32_e32 v5, v1, v2
	s_nop 0
	v_cndmask_b32_e32 v3, v3, v6, vcc
	v_cndmask_b32_e32 v1, v1, v5, vcc
	v_add_u32_e32 v5, 1, v3
	v_cmp_ge_u32_e32 vcc, v1, v2
	s_nop 1
	v_cndmask_b32_e32 v1, v3, v5, vcc
	v_mad_u64_u32 v[2:3], s[6:7], v2, v1, v[2:3]
	v_cmp_ne_u32_e32 vcc, v4, v2
	s_and_saveexec_b64 s[6:7], vcc
	s_xor_b64 s[6:7], exec, s[6:7]
	s_cbranch_execz .LBB0_729
	v_mov_b32_e32 v0, s4
	v_add_co_u32_e32 v2, vcc, 0x103000, v0
	v_mov_b32_e32 v0, s5
	s_nop 0
	v_addc_co_u32_e32 v3, vcc, 0, v0, vcc
	global_load_dword v0, v[2:3], off offset:1280 sc1
	s_add_u32 s12, s4, 0x103500
	s_addc_u32 s13, s5, 0
	s_waitcnt vmcnt(0) lgkmcnt(0)
	v_cmp_eq_u32_e32 vcc, v0, v1
	s_and_saveexec_b64 s[8:9], vcc
	s_cbranch_execz .LBB0_728
	s_add_u32 s10, s4, 0x100200
	s_addc_u32 s11, s5, 0
	s_mov_b32 s15, 1
	s_mov_b64 s[16:17], 0
	s_branch .LBB0_720

.LBB0_744:
	s_or_b64 exec, exec, s[4:5]
	v_mov_b32_e32 v0, s14
	v_add_co_u32_e32 v0, vcc, 0x2000, v0
	v_mov_b32_e32 v1, s3
	s_nop 0
	v_addc_co_u32_e32 v1, vcc, 0, v1, vcc
	v_mov_b32_e32 v2, 1
	s_waitcnt vmcnt(0) lgkmcnt(0)
	buffer_inv sc1
	s_waitcnt vmcnt(0)

.LBB0_1283:
	s_lshl_b32 s0, s0, 8
	s_add_u32 s0, s4, s0
	s_addc_u32 s2, s5, 0
	v_mov_b32_e32 v1, s0
	v_add_co_u32_e32 v4, vcc, 0x101000, v1
	v_mov_b32_e32 v1, s2
	s_nop 0
	v_addc_co_u32_e32 v5, vcc, 0, v1, vcc
	v_mov_b32_e32 v1, 1
	global_atomic_add v1, v[4:5], v1, off offset:1024 sc0
	v_cvt_f32_u32_e32 v3, v2
	v_sub_u32_e32 v4, 0, v2
	s_add_u32 s1, s0, 0x100000
	s_addc_u32 s0, s2, 0
	v_rcp_iflag_f32_e32 v3, v3
	s_nop 0
	v_mul_f32_e32 v3, 0x4f7ffffe, v3
	v_cvt_u32_f32_e32 v3, v3
	v_mul_lo_u32 v4, v4, v3
	v_mul_hi_u32 v4, v3, v4
	v_add_u32_e32 v3, v3, v4
	s_waitcnt vmcnt(0) lgkmcnt(0)
	v_mul_hi_u32 v3, v1, v3
	v_mul_lo_u32 v5, v3, v2
	v_add_u32_e32 v4, 1, v1
	v_sub_u32_e32 v1, v1, v5
	v_add_u32_e32 v6, 1, v3
	v_cmp_ge_u32_e32 vcc, v1, v2
	v_sub_u32_e32 v5, v1, v2
	s_nop 0
	v_cndmask_b32_e32 v3, v3, v6, vcc
	v_cndmask_b32_e32 v1, v1, v5, vcc
	v_add_u32_e32 v5, 1, v3
	v_cmp_ge_u32_e32 vcc, v1, v2
	s_nop 1
	v_cndmask_b32_e32 v1, v3, v5, vcc
	v_mad_u64_u32 v[2:3], s[2:3], v2, v1, v[2:3]
	v_cmp_ne_u32_e32 vcc, v4, v2
	s_and_saveexec_b64 s[2:3], vcc
	s_xor_b64 s[6:7], exec, s[2:3]
	s_cbranch_execz .LBB0_1296
	v_mov_b32_e32 v0, s4
	v_add_co_u32_e32 v2, vcc, 0x103000, v0
	v_mov_b32_e32 v0, s5
	s_nop 0
	v_addc_co_u32_e32 v3, vcc, 0, v0, vcc
	global_load_dword v0, v[2:3], off offset:1280 sc1
	s_add_u32 s12, s4, 0x103500
	s_addc_u32 s13, s5, 0
	s_waitcnt vmcnt(0) lgkmcnt(0)
	v_cmp_eq_u32_e32 vcc, v0, v1
	s_and_saveexec_b64 s[8:9], vcc
	s_cbranch_execz .LBB0_1295
	s_add_u32 s10, s4, 0x100200
	s_addc_u32 s11, s5, 0
	s_mov_b32 s2, 1
	s_mov_b64 s[16:17], 0
	s_branch .LBB0_1287

.LBB0_1311:
	s_or_b64 exec, exec, s[4:5]
	v_mov_b32_e32 v0, s1
	v_add_co_u32_e32 v0, vcc, 0x2000, v0
	v_mov_b32_e32 v1, s0
	s_nop 0
	v_addc_co_u32_e32 v1, vcc, 0, v1, vcc
	v_mov_b32_e32 v2, 1
	s_waitcnt vmcnt(0) lgkmcnt(0)
	buffer_inv sc1
	s_waitcnt vmcnt(0)

.LBB0_1433:
	s_lshl_b32 s0, s0, 8
	s_add_u32 s0, s4, s0
	s_addc_u32 s2, s5, 0
	v_mov_b32_e32 v1, s0
	v_add_co_u32_e32 v4, vcc, 0x101000, v1
	v_mov_b32_e32 v1, s2
	s_nop 0
	v_addc_co_u32_e32 v5, vcc, 0, v1, vcc
	v_mov_b32_e32 v1, 1
	global_atomic_add v1, v[4:5], v1, off offset:1024 sc0
	v_cvt_f32_u32_e32 v3, v2
	v_sub_u32_e32 v4, 0, v2
	s_add_u32 s1, s0, 0x100000
	s_addc_u32 s0, s2, 0
	v_rcp_iflag_f32_e32 v3, v3
	s_nop 0
	v_mul_f32_e32 v3, 0x4f7ffffe, v3
	v_cvt_u32_f32_e32 v3, v3
	v_mul_lo_u32 v4, v4, v3
	v_mul_hi_u32 v4, v3, v4
	v_add_u32_e32 v3, v3, v4
	s_waitcnt vmcnt(0) lgkmcnt(0)
	v_mul_hi_u32 v3, v1, v3
	v_mul_lo_u32 v5, v3, v2
	v_add_u32_e32 v4, 1, v1
	v_sub_u32_e32 v1, v1, v5
	v_add_u32_e32 v6, 1, v3
	v_cmp_ge_u32_e32 vcc, v1, v2
	v_sub_u32_e32 v5, v1, v2
	s_nop 0
	v_cndmask_b32_e32 v3, v3, v6, vcc
	v_cndmask_b32_e32 v1, v1, v5, vcc
	v_add_u32_e32 v5, 1, v3
	v_cmp_ge_u32_e32 vcc, v1, v2
	s_nop 1
	v_cndmask_b32_e32 v1, v3, v5, vcc
	v_mad_u64_u32 v[2:3], s[2:3], v2, v1, v[2:3]
	v_cmp_ne_u32_e32 vcc, v4, v2
	s_and_saveexec_b64 s[2:3], vcc
	s_xor_b64 s[6:7], exec, s[2:3]
	s_cbranch_execz .LBB0_1446
	v_mov_b32_e32 v0, s4
	v_add_co_u32_e32 v2, vcc, 0x103000, v0
	v_mov_b32_e32 v0, s5
	s_nop 0
	v_addc_co_u32_e32 v3, vcc, 0, v0, vcc
	global_load_dword v0, v[2:3], off offset:1280 sc1
	s_add_u32 s12, s4, 0x103500
	s_addc_u32 s13, s5, 0
	s_waitcnt vmcnt(0) lgkmcnt(0)
	v_cmp_eq_u32_e32 vcc, v0, v1
	s_and_saveexec_b64 s[8:9], vcc
	s_cbranch_execz .LBB0_1445
	s_add_u32 s10, s4, 0x100200
	s_addc_u32 s11, s5, 0
	s_mov_b32 s2, 1
	s_mov_b64 s[14:15], 0
	s_branch .LBB0_1437
